# P7 sample-row slab combine: 4 rows per iteration (36 loads in flight), g_a hoisted
# baseline (speedup 1.0000x reference)
.LBB0_256:
	v_and_b32_e32 v3, 0x7fc, v75
	v_lshlrev_b32_e32 v0, 2, v3
	global_load_dwordx4 v[60:63], v0, s[48:49]
	s_sub_u32 s52, s96, 0x4000000
	s_subb_u32 s53, s97, 0
	s_mov_b32 s13, 0
.Lp7c_loop:
	s_add_i32 s50, s12, s13
	s_add_i32 s50, s50, 0
	s_lshl_b32 s50, s50, 13
	v_add_u32_e32 v64, s50, v0
	global_load_dwordx4 v[20:23], v64, s[52:53]
	v_add_u32_e32 v2, 0x100000, v64
	global_load_dwordx4 v[24:27], v2, s[52:53]
	v_add_u32_e32 v2, 0x200000, v64
	global_load_dwordx4 v[28:31], v2, s[52:53]
	v_add_u32_e32 v2, 0x300000, v64
	global_load_dwordx4 v[32:35], v2, s[52:53]
	v_add_u32_e32 v2, 0x400000, v64
	global_load_dwordx4 v[36:39], v2, s[52:53]
	v_add_u32_e32 v2, 0x500000, v64
	global_load_dwordx4 v[40:43], v2, s[52:53]
	v_add_u32_e32 v2, 0x600000, v64
	global_load_dwordx4 v[44:47], v2, s[52:53]
	v_add_u32_e32 v2, 0x700000, v64
	global_load_dwordx4 v[48:51], v2, s[52:53]
	global_load_dwordx4 v[52:55], v64, s[22:23]
	s_add_i32 s50, s12, s13
	s_add_i32 s50, s50, 1
	s_lshl_b32 s50, s50, 13
	v_add_u32_e32 v65, s50, v0
	global_load_dwordx4 v[86:89], v65, s[52:53]
	v_add_u32_e32 v2, 0x100000, v65
	global_load_dwordx4 v[90:93], v2, s[52:53]
	v_add_u32_e32 v2, 0x200000, v65
	global_load_dwordx4 v[94:97], v2, s[52:53]
	v_add_u32_e32 v2, 0x300000, v65
	global_load_dwordx4 v[98:101], v2, s[52:53]
	v_add_u32_e32 v2, 0x400000, v65
	global_load_dwordx4 v[102:105], v2, s[52:53]
	v_add_u32_e32 v2, 0x500000, v65
	global_load_dwordx4 v[106:109], v2, s[52:53]
	v_add_u32_e32 v2, 0x600000, v65
	global_load_dwordx4 v[110:113], v2, s[52:53]
	v_add_u32_e32 v2, 0x700000, v65
	global_load_dwordx4 v[114:117], v2, s[52:53]
	global_load_dwordx4 v[118:121], v65, s[22:23]
	s_add_i32 s50, s12, s13
	s_add_i32 s50, s50, 2
	s_lshl_b32 s50, s50, 13
	v_add_u32_e32 v66, s50, v0
	global_load_dwordx4 v[122:125], v66, s[52:53]
	v_add_u32_e32 v2, 0x100000, v66
	global_load_dwordx4 v[126:129], v2, s[52:53]
	v_add_u32_e32 v2, 0x200000, v66
	global_load_dwordx4 v[130:133], v2, s[52:53]
	v_add_u32_e32 v2, 0x300000, v66
	global_load_dwordx4 v[134:137], v2, s[52:53]
	v_add_u32_e32 v2, 0x400000, v66
	global_load_dwordx4 v[138:141], v2, s[52:53]
	v_add_u32_e32 v2, 0x500000, v66
	global_load_dwordx4 v[142:145], v2, s[52:53]
	v_add_u32_e32 v2, 0x600000, v66
	global_load_dwordx4 v[146:149], v2, s[52:53]
	v_add_u32_e32 v2, 0x700000, v66
	global_load_dwordx4 v[150:153], v2, s[52:53]
	global_load_dwordx4 v[154:157], v66, s[22:23]
	s_add_i32 s50, s12, s13
	s_add_i32 s50, s50, 3
	s_lshl_b32 s50, s50, 13
	v_add_u32_e32 v67, s50, v0
	global_load_dwordx4 v[172:175], v67, s[52:53]
	v_add_u32_e32 v2, 0x100000, v67
	global_load_dwordx4 v[176:179], v2, s[52:53]
	v_add_u32_e32 v2, 0x200000, v67
	global_load_dwordx4 v[180:183], v2, s[52:53]
	v_add_u32_e32 v2, 0x300000, v67
	global_load_dwordx4 v[184:187], v2, s[52:53]
	v_add_u32_e32 v2, 0x400000, v67
	global_load_dwordx4 v[188:191], v2, s[52:53]
	v_add_u32_e32 v2, 0x500000, v67
	global_load_dwordx4 v[192:195], v2, s[52:53]
	v_add_u32_e32 v2, 0x600000, v67
	global_load_dwordx4 v[196:199], v2, s[52:53]
	v_add_u32_e32 v2, 0x700000, v67
	global_load_dwordx4 v[224:227], v2, s[52:53]
	global_load_dwordx4 v[228:231], v67, s[22:23]
	s_waitcnt vmcnt(35)
	v_pk_add_f32 v[14:15], v[20:21], 0 op_sel_hi:[1,0]
	v_pk_add_f32 v[12:13], v[22:23], 0 op_sel_hi:[1,0]
	s_waitcnt vmcnt(34)
	v_pk_add_f32 v[14:15], v[14:15], v[24:25]
	v_pk_add_f32 v[12:13], v[12:13], v[26:27]
	s_waitcnt vmcnt(33)
	v_pk_add_f32 v[14:15], v[14:15], v[28:29]
	v_pk_add_f32 v[12:13], v[12:13], v[30:31]
	s_waitcnt vmcnt(32)
	v_pk_add_f32 v[14:15], v[14:15], v[32:33]
	v_pk_add_f32 v[12:13], v[12:13], v[34:35]
	s_waitcnt vmcnt(31)
	v_pk_add_f32 v[14:15], v[14:15], v[36:37]
	v_pk_add_f32 v[12:13], v[12:13], v[38:39]
	s_waitcnt vmcnt(30)
	v_pk_add_f32 v[14:15], v[14:15], v[40:41]
	v_pk_add_f32 v[12:13], v[12:13], v[42:43]
	s_waitcnt vmcnt(29)
	v_pk_add_f32 v[14:15], v[14:15], v[44:45]
	v_pk_add_f32 v[12:13], v[12:13], v[46:47]
	s_waitcnt vmcnt(28)
	v_pk_add_f32 v[14:15], v[14:15], v[48:49]
	v_pk_add_f32 v[12:13], v[12:13], v[50:51]
	s_waitcnt vmcnt(27)
	v_pk_fma_f32 v[22:23], v[12:13], v[62:63], v[54:55]
	v_pk_fma_f32 v[20:21], v[14:15], v[60:61], v[52:53]
	s_waitcnt vmcnt(26)
	v_pk_add_f32 v[14:15], v[86:87], 0 op_sel_hi:[1,0]
	v_pk_add_f32 v[12:13], v[88:89], 0 op_sel_hi:[1,0]
	s_waitcnt vmcnt(25)
	v_pk_add_f32 v[14:15], v[14:15], v[90:91]
	v_pk_add_f32 v[12:13], v[12:13], v[92:93]
	s_waitcnt vmcnt(24)
	v_pk_add_f32 v[14:15], v[14:15], v[94:95]
	v_pk_add_f32 v[12:13], v[12:13], v[96:97]
	s_waitcnt vmcnt(23)
	v_pk_add_f32 v[14:15], v[14:15], v[98:99]
	v_pk_add_f32 v[12:13], v[12:13], v[100:101]
	s_waitcnt vmcnt(22)
	v_pk_add_f32 v[14:15], v[14:15], v[102:103]
	v_pk_add_f32 v[12:13], v[12:13], v[104:105]
	s_waitcnt vmcnt(21)
	v_pk_add_f32 v[14:15], v[14:15], v[106:107]
	v_pk_add_f32 v[12:13], v[12:13], v[108:109]
	s_waitcnt vmcnt(20)
	v_pk_add_f32 v[14:15], v[14:15], v[110:111]
	v_pk_add_f32 v[12:13], v[12:13], v[112:113]
	s_waitcnt vmcnt(19)
	v_pk_add_f32 v[14:15], v[14:15], v[114:115]
	v_pk_add_f32 v[12:13], v[12:13], v[116:117]
	s_waitcnt vmcnt(18)
	v_pk_fma_f32 v[88:89], v[12:13], v[62:63], v[120:121]
	v_pk_fma_f32 v[86:87], v[14:15], v[60:61], v[118:119]
	s_waitcnt vmcnt(17)
	v_pk_add_f32 v[14:15], v[122:123], 0 op_sel_hi:[1,0]
	v_pk_add_f32 v[12:13], v[124:125], 0 op_sel_hi:[1,0]
	s_waitcnt vmcnt(16)
	v_pk_add_f32 v[14:15], v[14:15], v[126:127]
	v_pk_add_f32 v[12:13], v[12:13], v[128:129]
	s_waitcnt vmcnt(15)
	v_pk_add_f32 v[14:15], v[14:15], v[130:131]
	v_pk_add_f32 v[12:13], v[12:13], v[132:133]
	s_waitcnt vmcnt(14)
	v_pk_add_f32 v[14:15], v[14:15], v[134:135]
	v_pk_add_f32 v[12:13], v[12:13], v[136:137]
	s_waitcnt vmcnt(13)
	v_pk_add_f32 v[14:15], v[14:15], v[138:139]
	v_pk_add_f32 v[12:13], v[12:13], v[140:141]
	s_waitcnt vmcnt(12)
	v_pk_add_f32 v[14:15], v[14:15], v[142:143]
	v_pk_add_f32 v[12:13], v[12:13], v[144:145]
	s_waitcnt vmcnt(11)
	v_pk_add_f32 v[14:15], v[14:15], v[146:147]
	v_pk_add_f32 v[12:13], v[12:13], v[148:149]
	s_waitcnt vmcnt(10)
	v_pk_add_f32 v[14:15], v[14:15], v[150:151]
	v_pk_add_f32 v[12:13], v[12:13], v[152:153]
	s_waitcnt vmcnt(9)
	v_pk_fma_f32 v[124:125], v[12:13], v[62:63], v[156:157]
	v_pk_fma_f32 v[122:123], v[14:15], v[60:61], v[154:155]
	s_waitcnt vmcnt(8)
	v_pk_add_f32 v[14:15], v[172:173], 0 op_sel_hi:[1,0]
	v_pk_add_f32 v[12:13], v[174:175], 0 op_sel_hi:[1,0]
	s_waitcnt vmcnt(7)
	v_pk_add_f32 v[14:15], v[14:15], v[176:177]
	v_pk_add_f32 v[12:13], v[12:13], v[178:179]
	s_waitcnt vmcnt(6)
	v_pk_add_f32 v[14:15], v[14:15], v[180:181]
	v_pk_add_f32 v[12:13], v[12:13], v[182:183]
	s_waitcnt vmcnt(5)
	v_pk_add_f32 v[14:15], v[14:15], v[184:185]
	v_pk_add_f32 v[12:13], v[12:13], v[186:187]
	s_waitcnt vmcnt(4)
	v_pk_add_f32 v[14:15], v[14:15], v[188:189]
	v_pk_add_f32 v[12:13], v[12:13], v[190:191]
	s_waitcnt vmcnt(3)
	v_pk_add_f32 v[14:15], v[14:15], v[192:193]
	v_pk_add_f32 v[12:13], v[12:13], v[194:195]
	s_waitcnt vmcnt(2)
	v_pk_add_f32 v[14:15], v[14:15], v[196:197]
	v_pk_add_f32 v[12:13], v[12:13], v[198:199]
	s_waitcnt vmcnt(1)
	v_pk_add_f32 v[14:15], v[14:15], v[224:225]
	v_pk_add_f32 v[12:13], v[12:13], v[226:227]
	s_waitcnt vmcnt(0)
	v_pk_fma_f32 v[174:175], v[12:13], v[62:63], v[230:231]
	v_pk_fma_f32 v[172:173], v[14:15], v[60:61], v[228:229]
	global_store_dwordx4 v64, v[20:23], s[22:23]
	global_store_dwordx4 v65, v[86:89], s[22:23]
	global_store_dwordx4 v66, v[122:125], s[22:23]
	global_store_dwordx4 v67, v[172:175], s[22:23]
	s_add_i32 s13, s13, 4
	s_cmp_lt_u32 s13, 16
	s_cbranch_scc1 .Lp7c_loop
